# in-projection k-loop: next-tile loads issued two per MFMA pair early, LDS stores 4/4/4 behind pairs 10-12
# baseline (speedup 1.0000x reference)
; #define MFMA(a, b, c) __builtin_amdgcn_mfma_f32_32x32x16_bf16((a), (b), (c), 0, 0, 0)
; template <bool SWAP, bool SSQ, class AF>
; DI void gemm_main(AF asrc, int m0, const u16* __restrict__ Bw, int ldb, int K, char* smem,
;                   f32x16 (&acc)[4][2], float ssq_eps, float (&rs)[4]) {
;     ...
;   for (int kt = 0; kt < nkt; ++kt) {
;     if (kt + 1 < nkt) gload(kt + 1);
;     __builtin_amdgcn_sched_barrier(0);
;     {
;       bf16x8 ar[3], br[2][2];
;       ar[0] = *(const bf16x8*)(pA);
;       ar[1] = *(const bf16x8*)(pA + 32 * 144);
;       br[0][0] = *(const bf16x8*)(pB);
;       br[0][1] = *(const bf16x8*)(pB + 32 * 144);
;       __builtin_amdgcn_sched_group_barrier(0x100, 4, 0);
; #pragma unroll
;       for (int t = 0; t < 16; ++t) {
;         const int ks = t >> 2, mi = t & 3;
;         if (t + 2 < 16) {
;           ar[(t + 2) % 3] = *(const bf16x8*)(pA + ((t + 2) & 3) * (32 * 144) + ((t + 2) >> 2) * 32);
;           if (mi == 1 && ks + 1 < 4) {
;             br[(ks + 1) & 1][0] = *(const bf16x8*)(pB + (ks + 1) * 32);
;             br[(ks + 1) & 1][1] = *(const bf16x8*)(pB + 32 * 144 + (ks + 1) * 32);
;             __builtin_amdgcn_sched_group_barrier(0x100, 3, 0);
;           } else {
;             __builtin_amdgcn_sched_group_barrier(0x100, 1, 0);
;           }
;         }
;         acc[mi][0] = SWAP ? MFMA(br[ks & 1][0], ar[t % 3], acc[mi][0]) : MFMA(ar[t % 3], br[ks & 1][0], acc[mi][0]);
;         acc[mi][1] = SWAP ? MFMA(br[ks & 1][1], ar[t % 3], acc[mi][1]) : MFMA(ar[t % 3], br[ks & 1][1], acc[mi][1]);
;         __builtin_amdgcn_sched_group_barrier(0x008, 2, 0);
;         if (SSQ) {
;           u32x4 u = __builtin_bit_cast(u32x4, ar[t % 3]);
; #pragma unroll
;           for (int j = 0; j < 4; ++j) rs[mi] = dot2bf(u[j], rs[mi]);
;         }
;       }
;     }
;     __syncthreads();
;     if (kt + 1 < nkt) sstore();
;     __syncthreads();
.LBB0_455:
	ds_read_b128 v[238:241], v137 offset:13824
	global_load_dwordx4 v[144:147], v198, s[34:35]
	global_load_dwordx4 v[150:153], v199, s[34:35]
	s_waitcnt lgkmcnt(3)
	v_mfma_f32_32x32x16_bf16 v[112:127], v[218:221], v[226:229], v[112:127]
	v_mfma_f32_32x32x16_bf16 v[96:111], v[222:225], v[226:229], v[96:111]
	ds_read_b128 v[226:229], v142 offset:36896
	ds_read_b128 v[242:245], v142 offset:41504
	global_load_dwordx4 v[154:157], v217, s[34:35]
	global_load_dwordx4 v[158:161], v250, s[34:35]
	s_waitcnt lgkmcnt(4)
	v_mfma_f32_32x32x16_bf16 v[80:95], v[218:221], v[230:233], v[80:95]
	v_mfma_f32_32x32x16_bf16 v[64:79], v[222:225], v[230:233], v[64:79]
	ds_read_b128 v[230:233], v137 offset:32
	global_load_dwordx4 v[162:165], v198, s[36:37]
	global_load_dwordx4 v[166:169], v199, s[36:37]
	s_waitcnt lgkmcnt(4)
	v_mfma_f32_32x32x16_bf16 v[48:63], v[218:221], v[234:237], v[48:63]
	v_mfma_f32_32x32x16_bf16 v[32:47], v[222:225], v[234:237], v[32:47]
	ds_read_b128 v[234:237], v137 offset:4640
	global_load_dwordx4 v[170:173], v217, s[36:37]
	global_load_dwordx4 v[174:177], v250, s[36:37]
	s_waitcnt lgkmcnt(4)
	v_mfma_f32_32x32x16_bf16 v[16:31], v[218:221], v[238:241], v[16:31]
	v_mfma_f32_32x32x16_bf16 v[0:15], v[222:225], v[238:241], v[0:15]
	ds_read_b128 v[218:221], v137 offset:9248
	ds_read_b128 v[222:225], v137 offset:13856
	global_load_dwordx4 v[178:181], v198, s[100:101]
	global_load_dwordx4 v[186:189], v199, s[100:101]
	s_waitcnt lgkmcnt(3)
	v_mfma_f32_32x32x16_bf16 v[112:127], v[226:229], v[230:233], v[112:127]
	v_mfma_f32_32x32x16_bf16 v[96:111], v[242:245], v[230:233], v[96:111]
	ds_read_b128 v[230:233], v142 offset:36928
	ds_read_b128 v[202:205], v142 offset:41536
	global_load_dwordx4 v[190:193], v217, s[100:101]
	global_load_dwordx4 v[194:197], v250, s[100:101]
	s_waitcnt lgkmcnt(4)
	v_mfma_f32_32x32x16_bf16 v[80:95], v[226:229], v[234:237], v[80:95]
	v_mfma_f32_32x32x16_bf16 v[64:79], v[242:245], v[234:237], v[64:79]
	ds_read_b128 v[234:237], v137 offset:64
	ds_read_b128 v[206:209], v137 offset:4672
	s_waitcnt lgkmcnt(5)
	v_mfma_f32_32x32x16_bf16 v[48:63], v[226:229], v[218:221], v[48:63]
	v_mfma_f32_32x32x16_bf16 v[32:47], v[242:245], v[218:221], v[32:47]
	ds_read_b128 v[218:221], v137 offset:9280
	s_waitcnt lgkmcnt(5)
	v_mfma_f32_32x32x16_bf16 v[16:31], v[226:229], v[222:225], v[16:31]
	v_mfma_f32_32x32x16_bf16 v[0:15], v[242:245], v[222:225], v[0:15]
	ds_read_b128 v[226:229], v137 offset:13888
	ds_read_b128 v[246:249], v142 offset:36960
	ds_read_b128 v[238:241], v142 offset:41568
	s_waitcnt lgkmcnt(5)
	v_mfma_f32_32x32x16_bf16 v[112:127], v[230:233], v[234:237], v[112:127]
	v_mfma_f32_32x32x16_bf16 v[96:111], v[202:205], v[234:237], v[96:111]
	ds_read_b128 v[222:225], v137 offset:96
	ds_read_b128 v[234:237], v137 offset:4704
	s_waitcnt lgkmcnt(6)
	v_mfma_f32_32x32x16_bf16 v[80:95], v[230:233], v[206:209], v[80:95]
	v_mfma_f32_32x32x16_bf16 v[64:79], v[202:205], v[206:209], v[64:79]
	ds_read_b128 v[242:245], v137 offset:9312
	ds_read_b128 v[206:209], v137 offset:13920
	s_waitcnt lgkmcnt(0)
	s_barrier
	v_mfma_f32_32x32x16_bf16 v[48:63], v[230:233], v[218:221], v[48:63]
	v_mfma_f32_32x32x16_bf16 v[32:47], v[202:205], v[218:221], v[32:47]
	s_waitcnt vmcnt(11)
	ds_write_b128 v136, v[144:147]
	s_waitcnt vmcnt(10)
	ds_write_b128 v136, v[150:153] offset:4608
	s_waitcnt vmcnt(9)
	ds_write_b128 v136, v[154:157] offset:9216
	s_waitcnt vmcnt(8)
	ds_write_b128 v136, v[158:161] offset:13824
	v_mfma_f32_32x32x16_bf16 v[16:31], v[230:233], v[226:229], v[16:31]
	v_mfma_f32_32x32x16_bf16 v[0:15], v[202:205], v[226:229], v[0:15]
	s_waitcnt vmcnt(7)
	ds_write_b128 v136, v[162:165] offset:18432
	s_waitcnt vmcnt(6)
	ds_write_b128 v136, v[166:169] offset:23040
	s_waitcnt vmcnt(5)
	ds_write_b128 v136, v[170:173] offset:27648
	s_waitcnt vmcnt(4)
	ds_write_b128 v136, v[174:177] offset:32256
	v_mfma_f32_32x32x16_bf16 v[112:127], v[246:249], v[222:225], v[112:127]
	v_mfma_f32_32x32x16_bf16 v[96:111], v[238:241], v[222:225], v[96:111]
	s_waitcnt vmcnt(3)
	ds_write_b128 v136, v[178:181] offset:36864
	s_waitcnt vmcnt(2)
	ds_write_b128 v136, v[186:189] offset:41472
	s_waitcnt vmcnt(1)
	ds_write_b128 v136, v[190:193] offset:46080
	s_waitcnt vmcnt(0)
	ds_write_b128 v136, v[194:197] offset:50688
	v_mfma_f32_32x32x16_bf16 v[80:95], v[246:249], v[234:237], v[80:95]
	v_mfma_f32_32x32x16_bf16 v[64:79], v[238:241], v[234:237], v[64:79]
	s_waitcnt lgkmcnt(0)
	s_barrier
	ds_read_b128 v[218:221], v142 offset:36864
	ds_read_b128 v[222:225], v142 offset:41472
	ds_read_b128 v[226:229], v137
	ds_read_b128 v[230:233], v137 offset:4608
	ds_read_b128 v[234:237], v137 offset:9216
	v_mfma_f32_32x32x16_bf16 v[48:63], v[246:249], v[242:245], v[48:63]
	v_mfma_f32_32x32x16_bf16 v[32:47], v[238:241], v[242:245], v[32:47]
	v_mfma_f32_32x32x16_bf16 v[16:31], v[246:249], v[206:209], v[16:31]
	v_mfma_f32_32x32x16_bf16 v[0:15], v[238:241], v[206:209], v[0:15]
	s_add_u32 s34, s34, 0x80
	s_addc_u32 s35, s35, 0
	s_add_u32 s36, s36, 0x80
	s_addc_u32 s37, s37, 0
	s_add_u32 s100, s100, 0x80
	s_addc_u32 s101, s101, 0
	s_add_u32 s12, s12, 0x80
	s_cmpk_lg_i32 s12, 0xf80
	s_cbranch_scc1 .LBB0_455
; #define MFMA(a, b, c) __builtin_amdgcn_mfma_f32_32x32x16_bf16((a), (b), (c), 0, 0, 0)
; template <bool SWAP, bool SSQ, class AF>
; DI void gemm_main(AF asrc, int m0, const u16* __restrict__ Bw, int ldb, int K, char* smem,
;                   f32x16 (&acc)[4][2], float ssq_eps, float (&rs)[4]) {
;     ...
;       for (int t = 0; t < 16; ++t) {
;         const int ks = t >> 2, mi = t & 3;
;         if (t + 2 < 16) {
;           ar[(t + 2) % 3] = *(const bf16x8*)(pA + ((t + 2) & 3) * (32 * 144) + ((t + 2) >> 2) * 32);
;           if (mi == 1 && ks + 1 < 4) {
;             br[(ks + 1) & 1][0] = *(const bf16x8*)(pB + (ks + 1) * 32);
;             br[(ks + 1) & 1][1] = *(const bf16x8*)(pB + 32 * 144 + (ks + 1) * 32);
;             __builtin_amdgcn_sched_group_barrier(0x100, 3, 0);
;           } else {
;             __builtin_amdgcn_sched_group_barrier(0x100, 1, 0);
;           }
;         }
;         acc[mi][0] = SWAP ? MFMA(br[ks & 1][0], ar[t % 3], acc[mi][0]) : MFMA(ar[t % 3], br[ks & 1][0], acc[mi][0]);
;         acc[mi][1] = SWAP ? MFMA(br[ks & 1][1], ar[t % 3], acc[mi][1]) : MFMA(ar[t % 3], br[ks & 1][1], acc[mi][1]);
;         __builtin_amdgcn_sched_group_barrier(0x008, 2, 0);
;         if (SSQ) {
;           u32x4 u = __builtin_bit_cast(u32x4, ar[t % 3]);
; #pragma unroll
;           for (int j = 0; j < 4; ++j) rs[mi] = dot2bf(u[j], rs[mi]);
;         }
;       }
;     }
;     __syncthreads();
;     if (kt + 1 < nkt) sstore();
;     __syncthreads();
	ds_read_b128 v[138:141], v142 offset:36864
	ds_read_b128 v[154:157], v142 offset:41472
	ds_read_b128 v[144:147], v137
	ds_read_b128 v[150:153], v137 offset:4608
	ds_read_b128 v[158:161], v137 offset:9216
	s_or_b32 s65, s8, s55
	s_cmpk_gt_i32 s65, 0x153f
	s_waitcnt lgkmcnt(2)
	v_mfma_f32_32x32x16_bf16 v[112:127], v[138:141], v[144:147], v[112:127]
	v_mfma_f32_32x32x16_bf16 v[96:111], v[154:157], v[144:147], v[96:111]
	ds_read_b128 v[162:165], v142 offset:36896
	ds_read_b128 v[166:169], v142 offset:41504
	ds_read_b128 v[144:147], v137 offset:13824
	s_waitcnt lgkmcnt(4)
	v_mfma_f32_32x32x16_bf16 v[80:95], v[138:141], v[150:153], v[80:95]
	v_mfma_f32_32x32x16_bf16 v[64:79], v[154:157], v[150:153], v[64:79]
	ds_read_b128 v[150:153], v137 offset:32
	s_waitcnt lgkmcnt(4)
	v_mfma_f32_32x32x16_bf16 v[48:63], v[138:141], v[158:161], v[48:63]
	v_mfma_f32_32x32x16_bf16 v[32:47], v[154:157], v[158:161], v[32:47]
	ds_read_b128 v[158:161], v137 offset:4640
	s_waitcnt lgkmcnt(2)
	v_mfma_f32_32x32x16_bf16 v[16:31], v[138:141], v[144:147], v[16:31]
	v_mfma_f32_32x32x16_bf16 v[0:15], v[154:157], v[144:147], v[0:15]
	ds_read_b128 v[138:141], v137 offset:9248
	s_waitcnt lgkmcnt(2)
	v_mfma_f32_32x32x16_bf16 v[112:127], v[162:165], v[150:153], v[112:127]
	v_mfma_f32_32x32x16_bf16 v[96:111], v[166:169], v[150:153], v[96:111]
	ds_read_b128 v[150:153], v142 offset:36928
	ds_read_b128 v[154:157], v142 offset:41536
	ds_read_b128 v[144:147], v137 offset:13856
	s_waitcnt lgkmcnt(4)
	v_mfma_f32_32x32x16_bf16 v[80:95], v[162:165], v[158:161], v[80:95]
	v_mfma_f32_32x32x16_bf16 v[64:79], v[166:169], v[158:161], v[64:79]
	ds_read_b128 v[158:161], v137 offset:64
	s_waitcnt lgkmcnt(4)
	v_mfma_f32_32x32x16_bf16 v[48:63], v[162:165], v[138:141], v[48:63]
	v_mfma_f32_32x32x16_bf16 v[32:47], v[166:169], v[138:141], v[32:47]
	ds_read_b128 v[138:141], v137 offset:4672
	s_waitcnt lgkmcnt(2)
	v_mfma_f32_32x32x16_bf16 v[16:31], v[162:165], v[144:147], v[16:31]
	v_mfma_f32_32x32x16_bf16 v[0:15], v[166:169], v[144:147], v[0:15]
	ds_read_b128 v[144:147], v137 offset:9280
	s_waitcnt lgkmcnt(2)
	v_mfma_f32_32x32x16_bf16 v[112:127], v[150:153], v[158:161], v[112:127]
	v_mfma_f32_32x32x16_bf16 v[96:111], v[154:157], v[158:161], v[96:111]
	ds_read_b128 v[162:165], v142 offset:36960
	ds_read_b128 v[166:169], v142 offset:41568
	ds_read_b128 v[158:161], v137 offset:13888
	s_waitcnt lgkmcnt(4)
	v_mfma_f32_32x32x16_bf16 v[80:95], v[150:153], v[138:141], v[80:95]
	v_mfma_f32_32x32x16_bf16 v[64:79], v[154:157], v[138:141], v[64:79]
	ds_read_b128 v[138:141], v137 offset:96
	s_waitcnt lgkmcnt(4)
	v_mfma_f32_32x32x16_bf16 v[48:63], v[150:153], v[144:147], v[48:63]
	v_mfma_f32_32x32x16_bf16 v[32:47], v[154:157], v[144:147], v[32:47]
	ds_read_b128 v[142:145], v137 offset:4704
	s_waitcnt lgkmcnt(2)
	v_mfma_f32_32x32x16_bf16 v[16:31], v[150:153], v[158:161], v[16:31]
	v_mfma_f32_32x32x16_bf16 v[0:15], v[154:157], v[158:161], v[0:15]
	ds_read_b128 v[150:153], v137 offset:9312
	s_waitcnt lgkmcnt(2)
	v_mfma_f32_32x32x16_bf16 v[112:127], v[162:165], v[138:141], v[112:127]
	v_mfma_f32_32x32x16_bf16 v[96:111], v[166:169], v[138:141], v[96:111]
	ds_read_b128 v[136:139], v137 offset:13920
	s_waitcnt lgkmcnt(0)
	s_barrier
	s_barrier
	v_mfma_f32_32x32x16_bf16 v[80:95], v[162:165], v[142:145], v[80:95]
	v_mfma_f32_32x32x16_bf16 v[64:79], v[166:169], v[142:145], v[64:79]
	v_mfma_f32_32x32x16_bf16 v[48:63], v[162:165], v[150:153], v[48:63]
	v_mfma_f32_32x32x16_bf16 v[32:47], v[166:169], v[150:153], v[32:47]
	v_mfma_f32_32x32x16_bf16 v[16:31], v[162:165], v[136:139], v[16:31]
	v_mfma_f32_32x32x16_bf16 v[0:15], v[166:169], v[136:139], v[0:15]
	s_cbranch_scc1 .LBB0_450
	v_readlane_b32 s12, v254, 31
	v_readlane_b32 s13, v254, 32
	s_andn2_b64 vcc, exec, s[12:13]
	s_cbranch_vccnz .LBB0_459
; DI void phase_inproj(const Params& p, const GroupP& g, int l, char* smem, int vb) {
;     ...
;     if (l == 1) {
;       const float* sq = p.rowsq + (size_t)4 * 50432 + g.seq0 + m0 + wm * 128 + lr;
; #pragma unroll
;       for (int mi = 0; mi < 4; ++mi) {
;         const float r = __builtin_amdgcn_rsqf(sq[mi * 32] * (1.f / DM) + 1e-6f);
; #pragma unroll
;         for (int ni = 0; ni < 2; ++ni)
; #pragma unroll
;           for (int i = 0; i < 16; ++i) acc[mi][ni][i] *= r;
;       }
;     }
	v_lshl_add_u64 v[136:137], s[10:11], 2, v[132:133]
	global_load_dword v138, v[136:137], off
	s_waitcnt vmcnt(0)
	v_fmamk_f32 v138, v138, 0x3a000000, v215
	v_rsq_f32_e32 v138, v138
	s_nop 0
	v_pk_mul_f32 v[126:127], v[126:127], v[138:139] op_sel_hi:[1,0]
	v_pk_mul_f32 v[124:125], v[124:125], v[138:139] op_sel_hi:[1,0]
	v_pk_mul_f32 v[122:123], v[122:123], v[138:139] op_sel_hi:[1,0]
	v_pk_mul_f32 v[120:121], v[120:121], v[138:139] op_sel_hi:[1,0]
	v_pk_mul_f32 v[118:119], v[118:119], v[138:139] op_sel_hi:[1,0]
	v_pk_mul_f32 v[116:117], v[116:117], v[138:139] op_sel_hi:[1,0]
	v_pk_mul_f32 v[114:115], v[114:115], v[138:139] op_sel_hi:[1,0]
	v_pk_mul_f32 v[112:113], v[112:113], v[138:139] op_sel_hi:[1,0]
	v_pk_mul_f32 v[110:111], v[110:111], v[138:139] op_sel_hi:[1,0]
	v_pk_mul_f32 v[108:109], v[108:109], v[138:139] op_sel_hi:[1,0]
	v_pk_mul_f32 v[106:107], v[106:107], v[138:139] op_sel_hi:[1,0]
	v_pk_mul_f32 v[104:105], v[104:105], v[138:139] op_sel_hi:[1,0]
	v_pk_mul_f32 v[102:103], v[102:103], v[138:139] op_sel_hi:[1,0]
	v_pk_mul_f32 v[100:101], v[100:101], v[138:139] op_sel_hi:[1,0]
	v_pk_mul_f32 v[98:99], v[98:99], v[138:139] op_sel_hi:[1,0]
	v_pk_mul_f32 v[96:97], v[96:97], v[138:139] op_sel_hi:[1,0]
	global_load_dword v138, v[136:137], off offset:128
	s_waitcnt vmcnt(0)
	v_fmamk_f32 v138, v138, 0x3a000000, v215
	v_rsq_f32_e32 v138, v138
	s_nop 0
	v_pk_mul_f32 v[94:95], v[94:95], v[138:139] op_sel_hi:[1,0]
	v_pk_mul_f32 v[92:93], v[92:93], v[138:139] op_sel_hi:[1,0]
	v_pk_mul_f32 v[90:91], v[90:91], v[138:139] op_sel_hi:[1,0]
	v_pk_mul_f32 v[88:89], v[88:89], v[138:139] op_sel_hi:[1,0]
	v_pk_mul_f32 v[86:87], v[86:87], v[138:139] op_sel_hi:[1,0]
	v_pk_mul_f32 v[84:85], v[84:85], v[138:139] op_sel_hi:[1,0]
	v_pk_mul_f32 v[82:83], v[82:83], v[138:139] op_sel_hi:[1,0]
	v_pk_mul_f32 v[80:81], v[80:81], v[138:139] op_sel_hi:[1,0]
	v_pk_mul_f32 v[78:79], v[78:79], v[138:139] op_sel_hi:[1,0]
	v_pk_mul_f32 v[76:77], v[76:77], v[138:139] op_sel_hi:[1,0]
	v_pk_mul_f32 v[74:75], v[74:75], v[138:139] op_sel_hi:[1,0]
	v_pk_mul_f32 v[72:73], v[72:73], v[138:139] op_sel_hi:[1,0]
	v_pk_mul_f32 v[70:71], v[70:71], v[138:139] op_sel_hi:[1,0]
	v_pk_mul_f32 v[68:69], v[68:69], v[138:139] op_sel_hi:[1,0]
	v_pk_mul_f32 v[66:67], v[66:67], v[138:139] op_sel_hi:[1,0]
	v_pk_mul_f32 v[64:65], v[64:65], v[138:139] op_sel_hi:[1,0]
	global_load_dword v138, v[136:137], off offset:256
	s_waitcnt vmcnt(0)
	v_fmamk_f32 v138, v138, 0x3a000000, v215
	global_load_dword v136, v[136:137], off offset:384
	v_rsq_f32_e32 v138, v138
	s_waitcnt vmcnt(0)
	v_fmamk_f32 v136, v136, 0x3a000000, v215
	v_rsq_f32_e32 v136, v136
	v_pk_mul_f32 v[62:63], v[62:63], v[138:139] op_sel_hi:[1,0]
	v_pk_mul_f32 v[60:61], v[60:61], v[138:139] op_sel_hi:[1,0]
	v_pk_mul_f32 v[58:59], v[58:59], v[138:139] op_sel_hi:[1,0]
	v_pk_mul_f32 v[56:57], v[56:57], v[138:139] op_sel_hi:[1,0]
	v_pk_mul_f32 v[54:55], v[54:55], v[138:139] op_sel_hi:[1,0]
	v_pk_mul_f32 v[52:53], v[52:53], v[138:139] op_sel_hi:[1,0]
	v_pk_mul_f32 v[50:51], v[50:51], v[138:139] op_sel_hi:[1,0]
	v_pk_mul_f32 v[48:49], v[48:49], v[138:139] op_sel_hi:[1,0]
	v_pk_mul_f32 v[46:47], v[46:47], v[138:139] op_sel_hi:[1,0]
	v_pk_mul_f32 v[44:45], v[44:45], v[138:139] op_sel_hi:[1,0]
	v_pk_mul_f32 v[42:43], v[42:43], v[138:139] op_sel_hi:[1,0]
	v_pk_mul_f32 v[40:41], v[40:41], v[138:139] op_sel_hi:[1,0]
	v_pk_mul_f32 v[38:39], v[38:39], v[138:139] op_sel_hi:[1,0]
	v_pk_mul_f32 v[36:37], v[36:37], v[138:139] op_sel_hi:[1,0]
	v_pk_mul_f32 v[34:35], v[34:35], v[138:139] op_sel_hi:[1,0]
	v_pk_mul_f32 v[32:33], v[32:33], v[138:139] op_sel_hi:[1,0]
	v_pk_mul_f32 v[30:31], v[30:31], v[136:137] op_sel_hi:[1,0]
	v_pk_mul_f32 v[28:29], v[28:29], v[136:137] op_sel_hi:[1,0]
	v_pk_mul_f32 v[26:27], v[26:27], v[136:137] op_sel_hi:[1,0]
	v_pk_mul_f32 v[24:25], v[24:25], v[136:137] op_sel_hi:[1,0]
	v_pk_mul_f32 v[22:23], v[22:23], v[136:137] op_sel_hi:[1,0]
	v_pk_mul_f32 v[20:21], v[20:21], v[136:137] op_sel_hi:[1,0]
	v_pk_mul_f32 v[18:19], v[18:19], v[136:137] op_sel_hi:[1,0]
	v_pk_mul_f32 v[16:17], v[16:17], v[136:137] op_sel_hi:[1,0]
	v_pk_mul_f32 v[14:15], v[14:15], v[136:137] op_sel_hi:[1,0]
	v_pk_mul_f32 v[12:13], v[12:13], v[136:137] op_sel_hi:[1,0]
	v_pk_mul_f32 v[10:11], v[10:11], v[136:137] op_sel_hi:[1,0]
	v_pk_mul_f32 v[8:9], v[8:9], v[136:137] op_sel_hi:[1,0]
	v_pk_mul_f32 v[6:7], v[6:7], v[136:137] op_sel_hi:[1,0]
	v_pk_mul_f32 v[4:5], v[4:5], v[136:137] op_sel_hi:[1,0]
	v_pk_mul_f32 v[2:3], v[2:3], v[136:137] op_sel_hi:[1,0]
	v_pk_mul_f32 v[0:1], v[0:1], v[136:137] op_sel_hi:[1,0]

; #define MFMA(a, b, c) __builtin_amdgcn_mfma_f32_32x32x16_bf16((a), (b), (c), 0, 0, 0)
; template <bool SWAP, bool SSQ, class AF>
; DI void gemm_main(AF asrc, int m0, const u16* __restrict__ Bw, int ldb, int K, char* smem,
;                   f32x16 (&acc)[4][2], float ssq_eps, float (&rs)[4]) {
;     ...
;   for (int kt = 0; kt < nkt; ++kt) {
;     if (kt + 1 < nkt) gload(kt + 1);
;     __builtin_amdgcn_sched_barrier(0);
;     {
;       bf16x8 ar[3], br[2][2];
;       ar[0] = *(const bf16x8*)(pA);
;       ar[1] = *(const bf16x8*)(pA + 32 * 144);
;       br[0][0] = *(const bf16x8*)(pB);
;       br[0][1] = *(const bf16x8*)(pB + 32 * 144);
;       __builtin_amdgcn_sched_group_barrier(0x100, 4, 0);
; #pragma unroll
;       for (int t = 0; t < 16; ++t) {
;         const int ks = t >> 2, mi = t & 3;
;         if (t + 2 < 16) {
;           ar[(t + 2) % 3] = *(const bf16x8*)(pA + ((t + 2) & 3) * (32 * 144) + ((t + 2) >> 2) * 32);
;           if (mi == 1 && ks + 1 < 4) {
;             br[(ks + 1) & 1][0] = *(const bf16x8*)(pB + (ks + 1) * 32);
;             br[(ks + 1) & 1][1] = *(const bf16x8*)(pB + 32 * 144 + (ks + 1) * 32);
;             __builtin_amdgcn_sched_group_barrier(0x100, 3, 0);
;           } else {
;             __builtin_amdgcn_sched_group_barrier(0x100, 1, 0);
;           }
;         }
;         acc[mi][0] = SWAP ? MFMA(br[ks & 1][0], ar[t % 3], acc[mi][0]) : MFMA(ar[t % 3], br[ks & 1][0], acc[mi][0]);
;         acc[mi][1] = SWAP ? MFMA(br[ks & 1][1], ar[t % 3], acc[mi][1]) : MFMA(ar[t % 3], br[ks & 1][1], acc[mi][1]);
;         __builtin_amdgcn_sched_group_barrier(0x008, 2, 0);
;         if (SSQ) {
;           u32x4 u = __builtin_bit_cast(u32x4, ar[t % 3]);
; #pragma unroll
;           for (int j = 0; j < 4; ++j) rs[mi] = dot2bf(u[j], rs[mi]);
;         }
;       }
;     }
;     __syncthreads();
;     if (kt + 1 < nkt) sstore();
;     __syncthreads();
.LBB0_588:
	ds_read_b128 v[238:241], v137 offset:13824
	global_load_dwordx4 v[144:147], v198, s[34:35]
	global_load_dwordx4 v[150:153], v199, s[34:35]
	s_waitcnt lgkmcnt(3)
	v_mfma_f32_32x32x16_bf16 v[112:127], v[218:221], v[226:229], v[112:127]
	v_mfma_f32_32x32x16_bf16 v[96:111], v[222:225], v[226:229], v[96:111]
	ds_read_b128 v[226:229], v142 offset:36896
	ds_read_b128 v[242:245], v142 offset:41504
	global_load_dwordx4 v[154:157], v217, s[34:35]
	global_load_dwordx4 v[158:161], v250, s[34:35]
	s_waitcnt lgkmcnt(4)
	v_mfma_f32_32x32x16_bf16 v[80:95], v[218:221], v[230:233], v[80:95]
	v_mfma_f32_32x32x16_bf16 v[64:79], v[222:225], v[230:233], v[64:79]
	ds_read_b128 v[230:233], v137 offset:32
	global_load_dwordx4 v[162:165], v198, s[36:37]
	global_load_dwordx4 v[166:169], v199, s[36:37]
	s_waitcnt lgkmcnt(4)
	v_mfma_f32_32x32x16_bf16 v[48:63], v[218:221], v[234:237], v[48:63]
	v_mfma_f32_32x32x16_bf16 v[32:47], v[222:225], v[234:237], v[32:47]
	ds_read_b128 v[234:237], v137 offset:4640
	global_load_dwordx4 v[170:173], v217, s[36:37]
	global_load_dwordx4 v[174:177], v250, s[36:37]
	s_waitcnt lgkmcnt(4)
	v_mfma_f32_32x32x16_bf16 v[16:31], v[218:221], v[238:241], v[16:31]
	v_mfma_f32_32x32x16_bf16 v[0:15], v[222:225], v[238:241], v[0:15]
	ds_read_b128 v[218:221], v137 offset:9248
	ds_read_b128 v[222:225], v137 offset:13856
	global_load_dwordx4 v[178:181], v198, s[100:101]
	global_load_dwordx4 v[186:189], v199, s[100:101]
	s_waitcnt lgkmcnt(3)
	v_mfma_f32_32x32x16_bf16 v[112:127], v[226:229], v[230:233], v[112:127]
	v_mfma_f32_32x32x16_bf16 v[96:111], v[242:245], v[230:233], v[96:111]
	ds_read_b128 v[230:233], v142 offset:36928
	ds_read_b128 v[202:205], v142 offset:41536
	global_load_dwordx4 v[190:193], v217, s[100:101]
	global_load_dwordx4 v[194:197], v250, s[100:101]
	s_waitcnt lgkmcnt(4)
	v_mfma_f32_32x32x16_bf16 v[80:95], v[226:229], v[234:237], v[80:95]
	v_mfma_f32_32x32x16_bf16 v[64:79], v[242:245], v[234:237], v[64:79]
	ds_read_b128 v[234:237], v137 offset:64
	ds_read_b128 v[206:209], v137 offset:4672
	s_waitcnt lgkmcnt(5)
	v_mfma_f32_32x32x16_bf16 v[48:63], v[226:229], v[218:221], v[48:63]
	v_mfma_f32_32x32x16_bf16 v[32:47], v[242:245], v[218:221], v[32:47]
	ds_read_b128 v[218:221], v137 offset:9280
	s_waitcnt lgkmcnt(5)
	v_mfma_f32_32x32x16_bf16 v[16:31], v[226:229], v[222:225], v[16:31]
	v_mfma_f32_32x32x16_bf16 v[0:15], v[242:245], v[222:225], v[0:15]
	ds_read_b128 v[226:229], v137 offset:13888
	ds_read_b128 v[246:249], v142 offset:36960
	ds_read_b128 v[238:241], v142 offset:41568
	s_waitcnt lgkmcnt(5)
	v_mfma_f32_32x32x16_bf16 v[112:127], v[230:233], v[234:237], v[112:127]
	v_mfma_f32_32x32x16_bf16 v[96:111], v[202:205], v[234:237], v[96:111]
	ds_read_b128 v[222:225], v137 offset:96
	ds_read_b128 v[234:237], v137 offset:4704
	s_waitcnt lgkmcnt(6)
	v_mfma_f32_32x32x16_bf16 v[80:95], v[230:233], v[206:209], v[80:95]
	v_mfma_f32_32x32x16_bf16 v[64:79], v[202:205], v[206:209], v[64:79]
	ds_read_b128 v[242:245], v137 offset:9312
	ds_read_b128 v[206:209], v137 offset:13920
	s_waitcnt lgkmcnt(0)
	s_barrier
	v_mfma_f32_32x32x16_bf16 v[48:63], v[230:233], v[218:221], v[48:63]
	v_mfma_f32_32x32x16_bf16 v[32:47], v[202:205], v[218:221], v[32:47]
	s_waitcnt vmcnt(11)
	ds_write_b128 v136, v[144:147]
	s_waitcnt vmcnt(10)
	ds_write_b128 v136, v[150:153] offset:4608
	s_waitcnt vmcnt(9)
	ds_write_b128 v136, v[154:157] offset:9216
	s_waitcnt vmcnt(8)
	ds_write_b128 v136, v[158:161] offset:13824
	v_mfma_f32_32x32x16_bf16 v[16:31], v[230:233], v[226:229], v[16:31]
	v_mfma_f32_32x32x16_bf16 v[0:15], v[202:205], v[226:229], v[0:15]
	s_waitcnt vmcnt(7)
	ds_write_b128 v136, v[162:165] offset:18432
	s_waitcnt vmcnt(6)
	ds_write_b128 v136, v[166:169] offset:23040
	s_waitcnt vmcnt(5)
	ds_write_b128 v136, v[170:173] offset:27648
	s_waitcnt vmcnt(4)
	ds_write_b128 v136, v[174:177] offset:32256
	v_mfma_f32_32x32x16_bf16 v[112:127], v[246:249], v[222:225], v[112:127]
	v_mfma_f32_32x32x16_bf16 v[96:111], v[238:241], v[222:225], v[96:111]
	s_waitcnt vmcnt(3)
	ds_write_b128 v136, v[178:181] offset:36864
	s_waitcnt vmcnt(2)
	ds_write_b128 v136, v[186:189] offset:41472
	s_waitcnt vmcnt(1)
	ds_write_b128 v136, v[190:193] offset:46080
	s_waitcnt vmcnt(0)
	ds_write_b128 v136, v[194:197] offset:50688
	v_mfma_f32_32x32x16_bf16 v[80:95], v[246:249], v[234:237], v[80:95]
	v_mfma_f32_32x32x16_bf16 v[64:79], v[238:241], v[234:237], v[64:79]
	s_waitcnt lgkmcnt(0)
	s_barrier
	ds_read_b128 v[218:221], v142 offset:36864
	ds_read_b128 v[222:225], v142 offset:41472
	ds_read_b128 v[226:229], v137
	ds_read_b128 v[230:233], v137 offset:4608
	ds_read_b128 v[234:237], v137 offset:9216
	v_mfma_f32_32x32x16_bf16 v[48:63], v[246:249], v[242:245], v[48:63]
	v_mfma_f32_32x32x16_bf16 v[32:47], v[238:241], v[242:245], v[32:47]
	v_mfma_f32_32x32x16_bf16 v[16:31], v[246:249], v[206:209], v[16:31]
	v_mfma_f32_32x32x16_bf16 v[0:15], v[238:241], v[206:209], v[0:15]
	s_add_u32 s34, s34, 0x80
	s_addc_u32 s35, s35, 0
	s_add_u32 s36, s36, 0x80
	s_addc_u32 s37, s37, 0
	s_add_u32 s100, s100, 0x80
	s_addc_u32 s101, s101, 0
	s_add_u32 s12, s12, 0x80
	s_cmpk_lg_i32 s12, 0xf80
	s_cbranch_scc1 .LBB0_588
; #define MFMA(a, b, c) __builtin_amdgcn_mfma_f32_32x32x16_bf16((a), (b), (c), 0, 0, 0)
; template <bool SWAP, bool SSQ, class AF>
; DI void gemm_main(AF asrc, int m0, const u16* __restrict__ Bw, int ldb, int K, char* smem,
;                   f32x16 (&acc)[4][2], float ssq_eps, float (&rs)[4]) {
;     ...
;       for (int t = 0; t < 16; ++t) {
;         const int ks = t >> 2, mi = t & 3;
;         if (t + 2 < 16) {
;           ar[(t + 2) % 3] = *(const bf16x8*)(pA + ((t + 2) & 3) * (32 * 144) + ((t + 2) >> 2) * 32);
;           if (mi == 1 && ks + 1 < 4) {
;             br[(ks + 1) & 1][0] = *(const bf16x8*)(pB + (ks + 1) * 32);
;             br[(ks + 1) & 1][1] = *(const bf16x8*)(pB + 32 * 144 + (ks + 1) * 32);
;             __builtin_amdgcn_sched_group_barrier(0x100, 3, 0);
;           } else {
;             __builtin_amdgcn_sched_group_barrier(0x100, 1, 0);
;           }
;         }
;         acc[mi][0] = SWAP ? MFMA(br[ks & 1][0], ar[t % 3], acc[mi][0]) : MFMA(ar[t % 3], br[ks & 1][0], acc[mi][0]);
;         acc[mi][1] = SWAP ? MFMA(br[ks & 1][1], ar[t % 3], acc[mi][1]) : MFMA(ar[t % 3], br[ks & 1][1], acc[mi][1]);
;         __builtin_amdgcn_sched_group_barrier(0x008, 2, 0);
;         if (SSQ) {
;           u32x4 u = __builtin_bit_cast(u32x4, ar[t % 3]);
; #pragma unroll
;           for (int j = 0; j < 4; ++j) rs[mi] = dot2bf(u[j], rs[mi]);
;         }
;       }
;     }
;     __syncthreads();
;     if (kt + 1 < nkt) sstore();
;     __syncthreads();
	ds_read_b128 v[138:141], v142 offset:36864
	ds_read_b128 v[154:157], v142 offset:41472
	ds_read_b128 v[144:147], v137
	ds_read_b128 v[150:153], v137 offset:4608
	ds_read_b128 v[158:161], v137 offset:9216
	s_or_b32 s64, s8, s56
	s_cmpk_gt_i32 s64, 0x153f
	s_waitcnt lgkmcnt(2)
	v_mfma_f32_32x32x16_bf16 v[112:127], v[138:141], v[144:147], v[112:127]
	v_mfma_f32_32x32x16_bf16 v[96:111], v[154:157], v[144:147], v[96:111]
	ds_read_b128 v[162:165], v142 offset:36896
	ds_read_b128 v[166:169], v142 offset:41504
	ds_read_b128 v[144:147], v137 offset:13824
	s_waitcnt lgkmcnt(4)
	v_mfma_f32_32x32x16_bf16 v[80:95], v[138:141], v[150:153], v[80:95]
	v_mfma_f32_32x32x16_bf16 v[64:79], v[154:157], v[150:153], v[64:79]
	ds_read_b128 v[150:153], v137 offset:32
	s_waitcnt lgkmcnt(4)
	v_mfma_f32_32x32x16_bf16 v[48:63], v[138:141], v[158:161], v[48:63]
	v_mfma_f32_32x32x16_bf16 v[32:47], v[154:157], v[158:161], v[32:47]
	ds_read_b128 v[158:161], v137 offset:4640
	s_waitcnt lgkmcnt(2)
	v_mfma_f32_32x32x16_bf16 v[16:31], v[138:141], v[144:147], v[16:31]
	v_mfma_f32_32x32x16_bf16 v[0:15], v[154:157], v[144:147], v[0:15]
	ds_read_b128 v[138:141], v137 offset:9248
	s_waitcnt lgkmcnt(2)
	v_mfma_f32_32x32x16_bf16 v[112:127], v[162:165], v[150:153], v[112:127]
	v_mfma_f32_32x32x16_bf16 v[96:111], v[166:169], v[150:153], v[96:111]
	ds_read_b128 v[150:153], v142 offset:36928
	ds_read_b128 v[154:157], v142 offset:41536
	ds_read_b128 v[144:147], v137 offset:13856
	s_waitcnt lgkmcnt(4)
	v_mfma_f32_32x32x16_bf16 v[80:95], v[162:165], v[158:161], v[80:95]
	v_mfma_f32_32x32x16_bf16 v[64:79], v[166:169], v[158:161], v[64:79]
	ds_read_b128 v[158:161], v137 offset:64
	s_waitcnt lgkmcnt(4)
	v_mfma_f32_32x32x16_bf16 v[48:63], v[162:165], v[138:141], v[48:63]
	v_mfma_f32_32x32x16_bf16 v[32:47], v[166:169], v[138:141], v[32:47]
	ds_read_b128 v[138:141], v137 offset:4672
	s_waitcnt lgkmcnt(2)
	v_mfma_f32_32x32x16_bf16 v[16:31], v[162:165], v[144:147], v[16:31]
	v_mfma_f32_32x32x16_bf16 v[0:15], v[166:169], v[144:147], v[0:15]
	ds_read_b128 v[144:147], v137 offset:9280
	s_waitcnt lgkmcnt(2)
	v_mfma_f32_32x32x16_bf16 v[112:127], v[150:153], v[158:161], v[112:127]
	v_mfma_f32_32x32x16_bf16 v[96:111], v[154:157], v[158:161], v[96:111]
	ds_read_b128 v[162:165], v142 offset:36960
	ds_read_b128 v[166:169], v142 offset:41568
	ds_read_b128 v[158:161], v137 offset:13888
	s_waitcnt lgkmcnt(4)
	v_mfma_f32_32x32x16_bf16 v[80:95], v[150:153], v[138:141], v[80:95]
	v_mfma_f32_32x32x16_bf16 v[64:79], v[154:157], v[138:141], v[64:79]
	ds_read_b128 v[138:141], v137 offset:96
	s_waitcnt lgkmcnt(4)
	v_mfma_f32_32x32x16_bf16 v[48:63], v[150:153], v[144:147], v[48:63]
	v_mfma_f32_32x32x16_bf16 v[32:47], v[154:157], v[144:147], v[32:47]
	ds_read_b128 v[142:145], v137 offset:4704
	s_waitcnt lgkmcnt(2)
	v_mfma_f32_32x32x16_bf16 v[16:31], v[150:153], v[158:161], v[16:31]
	v_mfma_f32_32x32x16_bf16 v[0:15], v[154:157], v[158:161], v[0:15]
	ds_read_b128 v[150:153], v137 offset:9312
	s_waitcnt lgkmcnt(2)
	v_mfma_f32_32x32x16_bf16 v[112:127], v[162:165], v[138:141], v[112:127]
	v_mfma_f32_32x32x16_bf16 v[96:111], v[166:169], v[138:141], v[96:111]
	ds_read_b128 v[136:139], v137 offset:13920
	s_waitcnt lgkmcnt(0)
	s_barrier
	s_barrier
	v_mfma_f32_32x32x16_bf16 v[80:95], v[162:165], v[142:145], v[80:95]
	v_mfma_f32_32x32x16_bf16 v[64:79], v[166:169], v[142:145], v[64:79]
	v_mfma_f32_32x32x16_bf16 v[48:63], v[162:165], v[150:153], v[48:63]
	v_mfma_f32_32x32x16_bf16 v[32:47], v[166:169], v[150:153], v[32:47]
	v_mfma_f32_32x32x16_bf16 v[16:31], v[162:165], v[136:139], v[16:31]
	v_mfma_f32_32x32x16_bf16 v[0:15], v[166:169], v[136:139], v[0:15]
	s_cbranch_scc1 .LBB0_583
	v_readlane_b32 s12, v254, 31
	v_readlane_b32 s13, v254, 32
	s_andn2_b64 vcc, exec, s[12:13]
	s_cbranch_vccnz .LBB0_592
; DI void phase_inproj(const Params& p, const GroupP& g, int l, char* smem, int vb) {
;     ...
;     if (l == 1) {
;       const float* sq = p.rowsq + (size_t)4 * 50432 + g.seq0 + m0 + wm * 128 + lr;
; #pragma unroll
;       for (int mi = 0; mi < 4; ++mi) {
;         const float r = __builtin_amdgcn_rsqf(sq[mi * 32] * (1.f / DM) + 1e-6f);
; #pragma unroll
;         for (int ni = 0; ni < 2; ++ni)
; #pragma unroll
;           for (int i = 0; i < 16; ++i) acc[mi][ni][i] *= r;
;       }
;     }
	v_lshl_add_u64 v[136:137], s[10:11], 2, v[132:133]
	global_load_dword v138, v[136:137], off
	s_waitcnt vmcnt(0)
	v_fmamk_f32 v138, v138, 0x3a000000, v215
	v_rsq_f32_e32 v138, v138
	s_nop 0
	v_pk_mul_f32 v[126:127], v[126:127], v[138:139] op_sel_hi:[1,0]
	v_pk_mul_f32 v[124:125], v[124:125], v[138:139] op_sel_hi:[1,0]
	v_pk_mul_f32 v[122:123], v[122:123], v[138:139] op_sel_hi:[1,0]
	v_pk_mul_f32 v[120:121], v[120:121], v[138:139] op_sel_hi:[1,0]
	v_pk_mul_f32 v[118:119], v[118:119], v[138:139] op_sel_hi:[1,0]
	v_pk_mul_f32 v[116:117], v[116:117], v[138:139] op_sel_hi:[1,0]
	v_pk_mul_f32 v[114:115], v[114:115], v[138:139] op_sel_hi:[1,0]
	v_pk_mul_f32 v[112:113], v[112:113], v[138:139] op_sel_hi:[1,0]
	v_pk_mul_f32 v[110:111], v[110:111], v[138:139] op_sel_hi:[1,0]
	v_pk_mul_f32 v[108:109], v[108:109], v[138:139] op_sel_hi:[1,0]
	v_pk_mul_f32 v[106:107], v[106:107], v[138:139] op_sel_hi:[1,0]
	v_pk_mul_f32 v[104:105], v[104:105], v[138:139] op_sel_hi:[1,0]
	v_pk_mul_f32 v[102:103], v[102:103], v[138:139] op_sel_hi:[1,0]
	v_pk_mul_f32 v[100:101], v[100:101], v[138:139] op_sel_hi:[1,0]
	v_pk_mul_f32 v[98:99], v[98:99], v[138:139] op_sel_hi:[1,0]
	v_pk_mul_f32 v[96:97], v[96:97], v[138:139] op_sel_hi:[1,0]
	global_load_dword v138, v[136:137], off offset:128
	s_waitcnt vmcnt(0)
	v_fmamk_f32 v138, v138, 0x3a000000, v215
	v_rsq_f32_e32 v138, v138
	s_nop 0
	v_pk_mul_f32 v[94:95], v[94:95], v[138:139] op_sel_hi:[1,0]
	v_pk_mul_f32 v[92:93], v[92:93], v[138:139] op_sel_hi:[1,0]
	v_pk_mul_f32 v[90:91], v[90:91], v[138:139] op_sel_hi:[1,0]
	v_pk_mul_f32 v[88:89], v[88:89], v[138:139] op_sel_hi:[1,0]
	v_pk_mul_f32 v[86:87], v[86:87], v[138:139] op_sel_hi:[1,0]
	v_pk_mul_f32 v[84:85], v[84:85], v[138:139] op_sel_hi:[1,0]
	v_pk_mul_f32 v[82:83], v[82:83], v[138:139] op_sel_hi:[1,0]
	v_pk_mul_f32 v[80:81], v[80:81], v[138:139] op_sel_hi:[1,0]
	v_pk_mul_f32 v[78:79], v[78:79], v[138:139] op_sel_hi:[1,0]
	v_pk_mul_f32 v[76:77], v[76:77], v[138:139] op_sel_hi:[1,0]
	v_pk_mul_f32 v[74:75], v[74:75], v[138:139] op_sel_hi:[1,0]
	v_pk_mul_f32 v[72:73], v[72:73], v[138:139] op_sel_hi:[1,0]
	v_pk_mul_f32 v[70:71], v[70:71], v[138:139] op_sel_hi:[1,0]
	v_pk_mul_f32 v[68:69], v[68:69], v[138:139] op_sel_hi:[1,0]
	v_pk_mul_f32 v[66:67], v[66:67], v[138:139] op_sel_hi:[1,0]
	v_pk_mul_f32 v[64:65], v[64:65], v[138:139] op_sel_hi:[1,0]
	global_load_dword v138, v[136:137], off offset:256
	s_waitcnt vmcnt(0)
	v_fmamk_f32 v138, v138, 0x3a000000, v215
	global_load_dword v136, v[136:137], off offset:384
	v_rsq_f32_e32 v138, v138
	s_waitcnt vmcnt(0)
	v_fmamk_f32 v136, v136, 0x3a000000, v215
	v_rsq_f32_e32 v136, v136
	v_pk_mul_f32 v[62:63], v[62:63], v[138:139] op_sel_hi:[1,0]
	v_pk_mul_f32 v[60:61], v[60:61], v[138:139] op_sel_hi:[1,0]
	v_pk_mul_f32 v[58:59], v[58:59], v[138:139] op_sel_hi:[1,0]
	v_pk_mul_f32 v[56:57], v[56:57], v[138:139] op_sel_hi:[1,0]
	v_pk_mul_f32 v[54:55], v[54:55], v[138:139] op_sel_hi:[1,0]
	v_pk_mul_f32 v[52:53], v[52:53], v[138:139] op_sel_hi:[1,0]
	v_pk_mul_f32 v[50:51], v[50:51], v[138:139] op_sel_hi:[1,0]
	v_pk_mul_f32 v[48:49], v[48:49], v[138:139] op_sel_hi:[1,0]
	v_pk_mul_f32 v[46:47], v[46:47], v[138:139] op_sel_hi:[1,0]
	v_pk_mul_f32 v[44:45], v[44:45], v[138:139] op_sel_hi:[1,0]
	v_pk_mul_f32 v[42:43], v[42:43], v[138:139] op_sel_hi:[1,0]
	v_pk_mul_f32 v[40:41], v[40:41], v[138:139] op_sel_hi:[1,0]
	v_pk_mul_f32 v[38:39], v[38:39], v[138:139] op_sel_hi:[1,0]
	v_pk_mul_f32 v[36:37], v[36:37], v[138:139] op_sel_hi:[1,0]
	v_pk_mul_f32 v[34:35], v[34:35], v[138:139] op_sel_hi:[1,0]
	v_pk_mul_f32 v[32:33], v[32:33], v[138:139] op_sel_hi:[1,0]
	v_pk_mul_f32 v[30:31], v[30:31], v[136:137] op_sel_hi:[1,0]
	v_pk_mul_f32 v[28:29], v[28:29], v[136:137] op_sel_hi:[1,0]
	v_pk_mul_f32 v[26:27], v[26:27], v[136:137] op_sel_hi:[1,0]
	v_pk_mul_f32 v[24:25], v[24:25], v[136:137] op_sel_hi:[1,0]
	v_pk_mul_f32 v[22:23], v[22:23], v[136:137] op_sel_hi:[1,0]
	v_pk_mul_f32 v[20:21], v[20:21], v[136:137] op_sel_hi:[1,0]
	v_pk_mul_f32 v[18:19], v[18:19], v[136:137] op_sel_hi:[1,0]
	v_pk_mul_f32 v[16:17], v[16:17], v[136:137] op_sel_hi:[1,0]
	v_pk_mul_f32 v[14:15], v[14:15], v[136:137] op_sel_hi:[1,0]
	v_pk_mul_f32 v[12:13], v[12:13], v[136:137] op_sel_hi:[1,0]
	v_pk_mul_f32 v[10:11], v[10:11], v[136:137] op_sel_hi:[1,0]
	v_pk_mul_f32 v[8:9], v[8:9], v[136:137] op_sel_hi:[1,0]
	v_pk_mul_f32 v[6:7], v[6:7], v[136:137] op_sel_hi:[1,0]
	v_pk_mul_f32 v[4:5], v[4:5], v[136:137] op_sel_hi:[1,0]
	v_pk_mul_f32 v[2:3], v[2:3], v[136:137] op_sel_hi:[1,0]
	v_pk_mul_f32 v[0:1], v[0:1], v[136:137] op_sel_hi:[1,0]
